# v12 plus GEMM2 gate-ratio hook: all 16 gate loads issued up front with counted vmcnt waits (was 8 serialized load pairs)
# speedup vs baseline: 1.0123x; 1.0123x over previous
;     __device__ __forceinline__ bf16_t* G() const { return (bf16_t*)(ws + OFF_G); }
; __device__ __forceinline__ int opaque_tid() { int t = threadIdx.x; asm volatile("" : "+v"(t)); return t; }
; __device__ __forceinline__ float ub(unsigned w, int j) { return (float)((w >> (8 * j)) & 0xffu); }
;     __device__ __forceinline__ void operator()(int seg, f32x4 (&acc)[2][2][4][2]) const {
;         const int tid2 = opaque_tid(), lane2 = tid2 & 63, wid2 = __builtin_amdgcn_readfirstlane(tid2 >> 6), wr = wid2 >> 2, wc = wid2 & 3, fr = lane2 & 15, fq = lane2 >> 4;
; #pragma unroll
;         for (int bj = 0; bj < 2; bj++)
; #pragma unroll
;             for (int n = 0; n < 2; n++) {
;                 const int tk = tok0 + bj * 128 + wc * 32 + n * 16 + fr;
;                 const unsigned char* gprev = G + (size_t)tk * 3072 + (seg - 1) * 1024 + feat0 + wr * 64 + fq * 16;
; #pragma unroll
;                 for (int ai = 0; ai < 2; ai++) {
;                     const u32x4 gp = *(const u32x4*)(gprev + ai * 128), gn = *(const u32x4*)(gprev + 1024 + ai * 128);
; #pragma unroll
;                     for (int m = 0; m < 4; m++) {
;                         f32x4& v = acc[ai][bj][m][n];
;                         v[0] *= ub(gp[m], 0) * __builtin_amdgcn_rcpf(ub(gn[m], 0)); v[1] *= ub(gp[m], 1) * __builtin_amdgcn_rcpf(ub(gn[m], 1));
;                         v[2] *= ub(gp[m], 2) * __builtin_amdgcn_rcpf(ub(gn[m], 2)); v[3] *= ub(gp[m], 3) * __builtin_amdgcn_rcpf(ub(gn[m], 3));
;                     }
;                 }
.LBB0_572:
	s_add_i32 s54, s12, 2
	s_cmp_eq_u32 s8, 0
	s_cselect_b64 s[10:11], -1, 0
	s_and_b32 s13, s54, 6
	s_cmp_lg_u32 s13, 0
	s_cselect_b64 s[14:15], -1, 0
	s_or_b64 s[10:11], s[10:11], s[14:15]
	s_and_b64 vcc, exec, s[10:11]
	s_cbranch_vccnz .LBB0_574
	v_mov_b32_e32 v130, v168
	s_nop 0
	v_readfirstlane_b32 s10, v130
	s_lshr_b32 s11, s10, 1
	s_and_b32 s11, s11, 0x60
	v_and_b32_e32 v136, 48, v130
	s_ashr_i32 s10, s10, 2
	v_and_or_b32 v130, v130, 15, s11
	s_and_b32 s13, s10, 0xffffffc0
	v_or_b32_e32 v137, s0, v130
	s_ashr_i32 s14, s13, 31
	v_mad_i64_i32 v[130:131], s[10:11], v137, s90, 0
	s_add_u32 s10, s89, s8
	s_addc_u32 s11, s30, s9
	s_add_u32 s10, s10, s13
	v_or_b32_e32 v130, v130, v136
	s_addc_u32 s11, s11, s14
	v_lshl_add_u64 v[134:135], s[10:11], 0, v[130:131]
	v_add_co_u32_e32 v138, vcc, s91, v134
	s_nop 1
	v_addc_co_u32_e32 v139, vcc, 0, v135, vcc
	v_add_co_u32_e32 v134, vcc, s81, v134
	v_mov_b32_e32 v164, v137
	v_mad_i64_i32 v[164:165], s[14:15], v164, s90, 0
	v_or_b32_e32 v164, v164, v136
	v_lshl_add_u64 v[164:165], s[10:11], 0, v[164:165]
	v_add_co_u32_e32 v166, vcc, s91, v164
	s_nop 1
	v_addc_co_u32_e32 v167, vcc, 0, v165, vcc
	v_add_co_u32_e32 v164, vcc, s81, v164
	s_nop 1
	v_addc_co_u32_e32 v165, vcc, 0, v165, vcc
	global_load_dwordx4 v[192:195], v[166:167], off offset:3328
	global_load_dwordx4 v[196:199], v[164:165], off offset:256
	global_load_dwordx4 v[200:203], v[166:167], off offset:3456
	global_load_dwordx4 v[204:207], v[164:165], off offset:384
	v_or_b32_e32 v164, 0x10, v137
	v_mad_i64_i32 v[164:165], s[14:15], v164, s90, 0
	v_or_b32_e32 v164, v164, v136
	v_lshl_add_u64 v[164:165], s[10:11], 0, v[164:165]
	v_add_co_u32_e32 v166, vcc, s91, v164
	s_nop 1
	v_addc_co_u32_e32 v167, vcc, 0, v165, vcc
	v_add_co_u32_e32 v164, vcc, s81, v164
	s_nop 1
	v_addc_co_u32_e32 v165, vcc, 0, v165, vcc
	global_load_dwordx4 v[208:211], v[166:167], off offset:3328
	global_load_dwordx4 v[212:215], v[164:165], off offset:256
	global_load_dwordx4 v[216:219], v[166:167], off offset:3456
	global_load_dwordx4 v[220:223], v[164:165], off offset:384
	v_or_b32_e32 v164, 0x80, v137
	v_mad_i64_i32 v[164:165], s[14:15], v164, s90, 0
	v_or_b32_e32 v164, v164, v136
	v_lshl_add_u64 v[164:165], s[10:11], 0, v[164:165]
	v_add_co_u32_e32 v166, vcc, s91, v164
	s_nop 1
	v_addc_co_u32_e32 v167, vcc, 0, v165, vcc
	v_add_co_u32_e32 v164, vcc, s81, v164
	s_nop 1
	v_addc_co_u32_e32 v165, vcc, 0, v165, vcc
	global_load_dwordx4 v[224:227], v[166:167], off offset:3328
	global_load_dwordx4 v[228:231], v[164:165], off offset:256
	global_load_dwordx4 v[232:235], v[166:167], off offset:3456
	global_load_dwordx4 v[236:239], v[164:165], off offset:384
	v_or_b32_e32 v164, 0x90, v137
	v_mad_i64_i32 v[164:165], s[14:15], v164, s90, 0
	v_or_b32_e32 v164, v164, v136
	v_lshl_add_u64 v[164:165], s[10:11], 0, v[164:165]
	v_add_co_u32_e32 v166, vcc, s91, v164
	s_nop 1
	v_addc_co_u32_e32 v167, vcc, 0, v165, vcc
	v_add_co_u32_e32 v164, vcc, s81, v164
	s_nop 1
	v_addc_co_u32_e32 v165, vcc, 0, v165, vcc
	global_load_dwordx4 v[240:243], v[166:167], off offset:3328
	global_load_dwordx4 v[244:247], v[164:165], off offset:256
	global_load_dwordx4 v[156:159], v[166:167], off offset:3456
	global_load_dwordx4 v[160:163], v[164:165], off offset:384
	v_addc_co_u32_e32 v135, vcc, 0, v135, vcc
	s_waitcnt vmcnt(14)
	v_cvt_f32_ubyte1_e32 v155, v192
	v_cvt_f32_ubyte0_e32 v154, v192
	v_cvt_f32_ubyte3_e32 v153, v192
	v_cvt_f32_ubyte0_e32 v148, v196
	v_cvt_f32_ubyte1_e32 v149, v196
	v_rcp_iflag_f32_e32 v148, v148
	v_rcp_iflag_f32_e32 v149, v149
	v_cvt_f32_ubyte2_e32 v152, v192
	v_cvt_f32_ubyte0_e32 v130, v197
	v_cvt_f32_ubyte2_e32 v150, v196
	v_pk_mul_f32 v[148:149], v[148:149], v[154:155]
	v_cvt_f32_ubyte3_e32 v144, v196
	v_pk_mul_f32 v[126:127], v[126:127], v[148:149]
	v_rcp_iflag_f32_e32 v148, v130
	v_cvt_f32_ubyte1_e32 v130, v197
	v_rcp_iflag_f32_e32 v150, v150
	v_rcp_iflag_f32_e32 v151, v144
	v_rcp_iflag_f32_e32 v149, v130
	v_cvt_f32_ubyte2_e32 v130, v197
	v_rcp_iflag_f32_e32 v144, v130
	v_cvt_f32_ubyte3_e32 v130, v197
	v_rcp_iflag_f32_e32 v145, v130
	v_pk_mul_f32 v[150:151], v[150:151], v[152:153]
	v_cvt_f32_ubyte1_e32 v153, v193
	v_pk_mul_f32 v[128:129], v[128:129], v[150:151]
	v_cvt_f32_ubyte3_e32 v151, v193
	v_cvt_f32_ubyte2_e32 v150, v193
	v_cvt_f32_ubyte0_e32 v152, v193
	v_pk_mul_f32 v[130:131], v[148:149], v[152:153]
	v_pk_mul_f32 v[144:145], v[144:145], v[150:151]
	v_pk_mul_f32 v[118:119], v[118:119], v[130:131]
	v_pk_mul_f32 v[120:121], v[120:121], v[144:145]
	v_cvt_f32_ubyte0_e32 v130, v198
	v_cvt_f32_ubyte1_e32 v131, v198
	v_cvt_f32_ubyte2_e32 v144, v198
	v_cvt_f32_ubyte3_e32 v145, v198
	v_rcp_iflag_f32_e32 v130, v130
	v_rcp_iflag_f32_e32 v131, v131
	v_rcp_iflag_f32_e32 v144, v144
	v_rcp_iflag_f32_e32 v145, v145
	v_cvt_f32_ubyte3_e32 v149, v194
	v_cvt_f32_ubyte2_e32 v148, v194
	v_cvt_f32_ubyte1_e32 v151, v194
	v_cvt_f32_ubyte0_e32 v150, v194
	v_pk_mul_f32 v[130:131], v[130:131], v[150:151]
	v_pk_mul_f32 v[144:145], v[144:145], v[148:149]
	v_cvt_f32_ubyte2_e32 v132, v199
	v_pk_mul_f32 v[112:113], v[112:113], v[144:145]
	v_pk_mul_f32 v[110:111], v[110:111], v[130:131]
	v_cvt_f32_ubyte0_e32 v130, v199
	v_cvt_f32_ubyte1_e32 v131, v199
	v_rcp_iflag_f32_e32 v144, v132
	v_cvt_f32_ubyte3_e32 v132, v199
	v_rcp_iflag_f32_e32 v130, v130
	v_rcp_iflag_f32_e32 v131, v131
	v_rcp_iflag_f32_e32 v145, v132
	v_cvt_f32_ubyte3_e32 v147, v195
	v_cvt_f32_ubyte2_e32 v146, v195
	v_cvt_f32_ubyte1_e32 v149, v195
	v_cvt_f32_ubyte0_e32 v148, v195
	v_pk_mul_f32 v[130:131], v[130:131], v[148:149]
	v_pk_mul_f32 v[132:133], v[144:145], v[146:147]
	v_pk_mul_f32 v[102:103], v[102:103], v[130:131]
	v_pk_mul_f32 v[104:105], v[104:105], v[132:133]
	s_waitcnt vmcnt(12)
;     __device__ __forceinline__ bf16_t* G() const { return (bf16_t*)(ws + OFF_G); }
; __device__ __forceinline__ float ub(unsigned w, int j) { return (float)((w >> (8 * j)) & 0xffu); }
;     __device__ __forceinline__ void operator()(int seg, f32x4 (&acc)[2][2][4][2]) const {
;     ...
;                 const int tk = tok0 + bj * 128 + wc * 32 + n * 16 + fr;
;                 const unsigned char* gprev = G + (size_t)tk * 3072 + (seg - 1) * 1024 + feat0 + wr * 64 + fq * 16;
; #pragma unroll
;                 for (int ai = 0; ai < 2; ai++) {
;                     const u32x4 gp = *(const u32x4*)(gprev + ai * 128), gn = *(const u32x4*)(gprev + 1024 + ai * 128);
; #pragma unroll
;                     for (int m = 0; m < 4; m++) {
;                         f32x4& v = acc[ai][bj][m][n];
;                         v[0] *= ub(gp[m], 0) * __builtin_amdgcn_rcpf(ub(gn[m], 0)); v[1] *= ub(gp[m], 1) * __builtin_amdgcn_rcpf(ub(gn[m], 1));
;                         v[2] *= ub(gp[m], 2) * __builtin_amdgcn_rcpf(ub(gn[m], 2)); v[3] *= ub(gp[m], 3) * __builtin_amdgcn_rcpf(ub(gn[m], 3));
;                     }
;                 }
	v_cvt_f32_ubyte1_e32 v151, v200
	v_cvt_f32_ubyte0_e32 v134, v204
	v_cvt_f32_ubyte1_e32 v135, v204
	v_rcp_iflag_f32_e32 v134, v134
	v_rcp_iflag_f32_e32 v135, v135
	v_cvt_f32_ubyte2_e32 v138, v204
	v_cvt_f32_ubyte3_e32 v139, v204
	v_cvt_f32_ubyte0_e32 v150, v200
	v_rcp_iflag_f32_e32 v138, v138
	v_rcp_iflag_f32_e32 v139, v139
	v_cvt_f32_ubyte3_e32 v149, v200
	v_cvt_f32_ubyte2_e32 v148, v200
	v_pk_mul_f32 v[134:135], v[134:135], v[150:151]
	v_cvt_f32_ubyte0_e32 v130, v205
	v_pk_mul_f32 v[62:63], v[62:63], v[134:135]
	v_rcp_iflag_f32_e32 v134, v130
	v_cvt_f32_ubyte1_e32 v130, v205
	v_rcp_iflag_f32_e32 v135, v130
	v_pk_mul_f32 v[138:139], v[138:139], v[148:149]
	v_cvt_f32_ubyte2_e32 v130, v205
	v_pk_mul_f32 v[64:65], v[64:65], v[138:139]
	v_rcp_iflag_f32_e32 v138, v130
	v_cvt_f32_ubyte3_e32 v130, v205
	v_cvt_f32_ubyte1_e32 v149, v201
	v_cvt_f32_ubyte0_e32 v148, v201
	v_rcp_iflag_f32_e32 v139, v130
	v_cvt_f32_ubyte3_e32 v145, v201
	v_cvt_f32_ubyte2_e32 v144, v201
	v_pk_mul_f32 v[130:131], v[134:135], v[148:149]
	v_pk_mul_f32 v[134:135], v[138:139], v[144:145]
	v_pk_mul_f32 v[54:55], v[54:55], v[130:131]
	v_cvt_f32_ubyte0_e32 v130, v206
	v_cvt_f32_ubyte1_e32 v131, v206
	v_rcp_iflag_f32_e32 v130, v130
	v_rcp_iflag_f32_e32 v131, v131
	v_pk_mul_f32 v[56:57], v[56:57], v[134:135]
	v_cvt_f32_ubyte2_e32 v134, v206
	v_cvt_f32_ubyte3_e32 v135, v206
	v_cvt_f32_ubyte1_e32 v145, v202
	v_cvt_f32_ubyte0_e32 v144, v202
	v_rcp_iflag_f32_e32 v134, v134
	v_rcp_iflag_f32_e32 v135, v135
	v_pk_mul_f32 v[130:131], v[130:131], v[144:145]
	v_cvt_f32_ubyte3_e32 v139, v202
	v_pk_mul_f32 v[46:47], v[46:47], v[130:131]
	v_cvt_f32_ubyte0_e32 v130, v207
	v_cvt_f32_ubyte1_e32 v131, v207
	v_rcp_iflag_f32_e32 v130, v130
	v_rcp_iflag_f32_e32 v131, v131
	v_cvt_f32_ubyte2_e32 v138, v202
	v_pk_mul_f32 v[134:135], v[134:135], v[138:139]
	v_cvt_f32_ubyte2_e32 v132, v207
	v_pk_mul_f32 v[48:49], v[48:49], v[134:135]
	v_rcp_iflag_f32_e32 v134, v132
	v_cvt_f32_ubyte3_e32 v132, v207
	v_cvt_f32_ubyte1_e32 v145, v203
	v_cvt_f32_ubyte0_e32 v144, v203
	v_rcp_iflag_f32_e32 v135, v132
	v_pk_mul_f32 v[130:131], v[130:131], v[144:145]
	v_cvt_f32_ubyte3_e32 v139, v203
	v_pk_mul_f32 v[38:39], v[38:39], v[130:131]
	v_or_b32_e32 v130, 16, v137
	v_mad_i64_i32 v[130:131], s[14:15], v130, s90, 0
	v_cvt_f32_ubyte2_e32 v138, v203
	v_or_b32_e32 v130, v130, v136
	v_pk_mul_f32 v[132:133], v[134:135], v[138:139]
	v_lshl_add_u64 v[134:135], s[10:11], 0, v[130:131]
	v_add_co_u32_e32 v138, vcc, s91, v134
	v_pk_mul_f32 v[40:41], v[40:41], v[132:133]
	s_nop 0
	v_addc_co_u32_e32 v139, vcc, 0, v135, vcc
	v_add_co_u32_e32 v134, vcc, s81, v134
	v_addc_co_u32_e32 v135, vcc, 0, v135, vcc
	s_waitcnt vmcnt(10)
	v_cvt_f32_ubyte1_e32 v155, v208
	v_cvt_f32_ubyte0_e32 v154, v208
	v_cvt_f32_ubyte3_e32 v153, v208
	v_cvt_f32_ubyte0_e32 v148, v212
	v_cvt_f32_ubyte1_e32 v149, v212
	v_rcp_iflag_f32_e32 v148, v148
	v_rcp_iflag_f32_e32 v149, v149
	v_cvt_f32_ubyte2_e32 v152, v208
	v_cvt_f32_ubyte0_e32 v130, v213
	v_cvt_f32_ubyte2_e32 v150, v212
	v_pk_mul_f32 v[148:149], v[148:149], v[154:155]
	v_cvt_f32_ubyte3_e32 v144, v212
	v_pk_mul_f32 v[122:123], v[122:123], v[148:149]
	v_rcp_iflag_f32_e32 v148, v130
	v_cvt_f32_ubyte1_e32 v130, v213
	v_rcp_iflag_f32_e32 v150, v150
	v_rcp_iflag_f32_e32 v151, v144
	v_rcp_iflag_f32_e32 v149, v130
	v_cvt_f32_ubyte2_e32 v130, v213
	v_rcp_iflag_f32_e32 v144, v130
	v_cvt_f32_ubyte3_e32 v130, v213
	v_rcp_iflag_f32_e32 v145, v130
	v_pk_mul_f32 v[150:151], v[150:151], v[152:153]
	v_cvt_f32_ubyte1_e32 v153, v209
	v_pk_mul_f32 v[124:125], v[124:125], v[150:151]
	v_cvt_f32_ubyte3_e32 v151, v209
	v_cvt_f32_ubyte2_e32 v150, v209
	v_cvt_f32_ubyte0_e32 v152, v209
	v_pk_mul_f32 v[130:131], v[148:149], v[152:153]
	v_pk_mul_f32 v[144:145], v[144:145], v[150:151]
	v_pk_mul_f32 v[114:115], v[114:115], v[130:131]
	v_pk_mul_f32 v[116:117], v[116:117], v[144:145]
	v_cvt_f32_ubyte0_e32 v130, v214
	v_cvt_f32_ubyte1_e32 v131, v214
	v_cvt_f32_ubyte2_e32 v144, v214
	v_cvt_f32_ubyte3_e32 v145, v214
	v_rcp_iflag_f32_e32 v130, v130
	v_rcp_iflag_f32_e32 v131, v131
	v_rcp_iflag_f32_e32 v144, v144
	v_rcp_iflag_f32_e32 v145, v145
	v_cvt_f32_ubyte3_e32 v149, v210
	v_cvt_f32_ubyte2_e32 v148, v210
	v_cvt_f32_ubyte1_e32 v151, v210
	v_cvt_f32_ubyte0_e32 v150, v210
	v_pk_mul_f32 v[130:131], v[130:131], v[150:151]
	v_pk_mul_f32 v[144:145], v[144:145], v[148:149]
	v_cvt_f32_ubyte2_e32 v132, v215
	v_pk_mul_f32 v[108:109], v[108:109], v[144:145]
	v_pk_mul_f32 v[106:107], v[106:107], v[130:131]
	v_cvt_f32_ubyte0_e32 v130, v215
	v_cvt_f32_ubyte1_e32 v131, v215
	v_rcp_iflag_f32_e32 v144, v132
	v_cvt_f32_ubyte3_e32 v132, v215
	v_rcp_iflag_f32_e32 v130, v130
	v_rcp_iflag_f32_e32 v131, v131
	v_rcp_iflag_f32_e32 v145, v132
	v_cvt_f32_ubyte3_e32 v147, v211
	v_cvt_f32_ubyte2_e32 v146, v211
	v_cvt_f32_ubyte1_e32 v149, v211
	v_cvt_f32_ubyte0_e32 v148, v211
	v_pk_mul_f32 v[130:131], v[130:131], v[148:149]
	v_pk_mul_f32 v[132:133], v[144:145], v[146:147]
	v_pk_mul_f32 v[98:99], v[98:99], v[130:131]
	v_pk_mul_f32 v[100:101], v[100:101], v[132:133]
	s_waitcnt vmcnt(8)
;     __device__ __forceinline__ bf16_t* G() const { return (bf16_t*)(ws + OFF_G); }
; __device__ __forceinline__ float ub(unsigned w, int j) { return (float)((w >> (8 * j)) & 0xffu); }
;     __device__ __forceinline__ void operator()(int seg, f32x4 (&acc)[2][2][4][2]) const {
;     ...
;                 const int tk = tok0 + bj * 128 + wc * 32 + n * 16 + fr;
;                 const unsigned char* gprev = G + (size_t)tk * 3072 + (seg - 1) * 1024 + feat0 + wr * 64 + fq * 16;
; #pragma unroll
;                 for (int ai = 0; ai < 2; ai++) {
;                     const u32x4 gp = *(const u32x4*)(gprev + ai * 128), gn = *(const u32x4*)(gprev + 1024 + ai * 128);
; #pragma unroll
;                     for (int m = 0; m < 4; m++) {
;                         f32x4& v = acc[ai][bj][m][n];
;                         v[0] *= ub(gp[m], 0) * __builtin_amdgcn_rcpf(ub(gn[m], 0)); v[1] *= ub(gp[m], 1) * __builtin_amdgcn_rcpf(ub(gn[m], 1));
;                         v[2] *= ub(gp[m], 2) * __builtin_amdgcn_rcpf(ub(gn[m], 2)); v[3] *= ub(gp[m], 3) * __builtin_amdgcn_rcpf(ub(gn[m], 3));
;                     }
;                 }
	v_cvt_f32_ubyte1_e32 v151, v216
	v_cvt_f32_ubyte0_e32 v134, v220
	v_cvt_f32_ubyte1_e32 v135, v220
	v_rcp_iflag_f32_e32 v134, v134
	v_rcp_iflag_f32_e32 v135, v135
	v_cvt_f32_ubyte2_e32 v138, v220
	v_cvt_f32_ubyte3_e32 v139, v220
	v_cvt_f32_ubyte0_e32 v150, v216
	v_rcp_iflag_f32_e32 v138, v138
	v_rcp_iflag_f32_e32 v139, v139
	v_cvt_f32_ubyte3_e32 v149, v216
	v_cvt_f32_ubyte2_e32 v148, v216
	v_pk_mul_f32 v[134:135], v[134:135], v[150:151]
	v_cvt_f32_ubyte0_e32 v130, v221
	v_pk_mul_f32 v[58:59], v[58:59], v[134:135]
	v_rcp_iflag_f32_e32 v134, v130
	v_cvt_f32_ubyte1_e32 v130, v221
	v_rcp_iflag_f32_e32 v135, v130
	v_pk_mul_f32 v[138:139], v[138:139], v[148:149]
	v_cvt_f32_ubyte2_e32 v130, v221
	v_pk_mul_f32 v[60:61], v[60:61], v[138:139]
	v_rcp_iflag_f32_e32 v138, v130
	v_cvt_f32_ubyte3_e32 v130, v221
	v_cvt_f32_ubyte1_e32 v149, v217
	v_cvt_f32_ubyte0_e32 v148, v217
	v_rcp_iflag_f32_e32 v139, v130
	v_cvt_f32_ubyte3_e32 v145, v217
	v_cvt_f32_ubyte2_e32 v144, v217
	v_pk_mul_f32 v[130:131], v[134:135], v[148:149]
	v_pk_mul_f32 v[134:135], v[138:139], v[144:145]
	v_pk_mul_f32 v[50:51], v[50:51], v[130:131]
	v_cvt_f32_ubyte0_e32 v130, v222
	v_cvt_f32_ubyte1_e32 v131, v222
	v_rcp_iflag_f32_e32 v130, v130
	v_rcp_iflag_f32_e32 v131, v131
	v_pk_mul_f32 v[52:53], v[52:53], v[134:135]
	v_cvt_f32_ubyte2_e32 v134, v222
	v_cvt_f32_ubyte3_e32 v135, v222
	v_cvt_f32_ubyte1_e32 v145, v218
	v_cvt_f32_ubyte0_e32 v144, v218
	v_rcp_iflag_f32_e32 v134, v134
	v_rcp_iflag_f32_e32 v135, v135
	v_pk_mul_f32 v[130:131], v[130:131], v[144:145]
	v_cvt_f32_ubyte3_e32 v139, v218
	v_pk_mul_f32 v[42:43], v[42:43], v[130:131]
	v_cvt_f32_ubyte0_e32 v130, v223
	v_cvt_f32_ubyte1_e32 v131, v223
	v_rcp_iflag_f32_e32 v130, v130
	v_rcp_iflag_f32_e32 v131, v131
	v_cvt_f32_ubyte2_e32 v138, v218
	v_pk_mul_f32 v[134:135], v[134:135], v[138:139]
	v_cvt_f32_ubyte2_e32 v132, v223
	v_pk_mul_f32 v[44:45], v[44:45], v[134:135]
	v_rcp_iflag_f32_e32 v134, v132
	v_cvt_f32_ubyte3_e32 v132, v223
	v_cvt_f32_ubyte1_e32 v145, v219
	v_cvt_f32_ubyte0_e32 v144, v219
	v_rcp_iflag_f32_e32 v135, v132
	v_pk_mul_f32 v[130:131], v[130:131], v[144:145]
	v_cvt_f32_ubyte3_e32 v139, v219
	v_pk_mul_f32 v[34:35], v[34:35], v[130:131]
	v_or_b32_e32 v130, 0x80, v137
	v_mad_i64_i32 v[130:131], s[14:15], v130, s90, 0
	v_cvt_f32_ubyte2_e32 v138, v219
	v_or_b32_e32 v130, v130, v136
	v_pk_mul_f32 v[132:133], v[134:135], v[138:139]
	v_lshl_add_u64 v[134:135], s[10:11], 0, v[130:131]
	v_add_co_u32_e32 v138, vcc, s91, v134
	v_pk_mul_f32 v[36:37], v[36:37], v[132:133]
	s_nop 0
	v_addc_co_u32_e32 v139, vcc, 0, v135, vcc
	v_add_co_u32_e32 v134, vcc, s81, v134
	v_addc_co_u32_e32 v135, vcc, 0, v135, vcc
	s_waitcnt vmcnt(6)
	v_cvt_f32_ubyte1_e32 v155, v224
	v_cvt_f32_ubyte0_e32 v154, v224
	v_cvt_f32_ubyte3_e32 v153, v224
	v_cvt_f32_ubyte0_e32 v148, v228
	v_cvt_f32_ubyte1_e32 v149, v228
	v_rcp_iflag_f32_e32 v148, v148
	v_rcp_iflag_f32_e32 v149, v149
	v_cvt_f32_ubyte2_e32 v152, v224
	v_cvt_f32_ubyte0_e32 v130, v229
	v_cvt_f32_ubyte2_e32 v150, v228
	v_pk_mul_f32 v[148:149], v[148:149], v[154:155]
	v_cvt_f32_ubyte3_e32 v144, v228
	v_pk_mul_f32 v[94:95], v[94:95], v[148:149]
	v_rcp_iflag_f32_e32 v148, v130
	v_cvt_f32_ubyte1_e32 v130, v229
	v_rcp_iflag_f32_e32 v150, v150
	v_rcp_iflag_f32_e32 v151, v144
	v_rcp_iflag_f32_e32 v149, v130
	v_cvt_f32_ubyte2_e32 v130, v229
	v_rcp_iflag_f32_e32 v144, v130
	v_cvt_f32_ubyte3_e32 v130, v229
	v_rcp_iflag_f32_e32 v145, v130
	v_pk_mul_f32 v[150:151], v[150:151], v[152:153]
	v_cvt_f32_ubyte1_e32 v153, v225
	v_pk_mul_f32 v[96:97], v[96:97], v[150:151]
	v_cvt_f32_ubyte3_e32 v151, v225
	v_cvt_f32_ubyte2_e32 v150, v225
	v_cvt_f32_ubyte0_e32 v152, v225
	v_pk_mul_f32 v[130:131], v[148:149], v[152:153]
	v_pk_mul_f32 v[144:145], v[144:145], v[150:151]
	v_pk_mul_f32 v[86:87], v[86:87], v[130:131]
	v_pk_mul_f32 v[88:89], v[88:89], v[144:145]
	v_cvt_f32_ubyte0_e32 v130, v230
	v_cvt_f32_ubyte1_e32 v131, v230
	v_cvt_f32_ubyte2_e32 v144, v230
	v_cvt_f32_ubyte3_e32 v145, v230
	v_rcp_iflag_f32_e32 v130, v130
	v_rcp_iflag_f32_e32 v131, v131
	v_rcp_iflag_f32_e32 v144, v144
	v_rcp_iflag_f32_e32 v145, v145
	v_cvt_f32_ubyte3_e32 v149, v226
	v_cvt_f32_ubyte2_e32 v148, v226
	v_cvt_f32_ubyte1_e32 v151, v226
	v_cvt_f32_ubyte0_e32 v150, v226
	v_pk_mul_f32 v[130:131], v[130:131], v[150:151]
	v_pk_mul_f32 v[144:145], v[144:145], v[148:149]
	v_cvt_f32_ubyte2_e32 v132, v231
	v_pk_mul_f32 v[80:81], v[80:81], v[144:145]
	v_pk_mul_f32 v[78:79], v[78:79], v[130:131]
	v_cvt_f32_ubyte0_e32 v130, v231
	v_cvt_f32_ubyte1_e32 v131, v231
	v_rcp_iflag_f32_e32 v144, v132
	v_cvt_f32_ubyte3_e32 v132, v231
	v_rcp_iflag_f32_e32 v130, v130
	v_rcp_iflag_f32_e32 v131, v131
	v_rcp_iflag_f32_e32 v145, v132
	v_cvt_f32_ubyte3_e32 v147, v227
	v_cvt_f32_ubyte2_e32 v146, v227
	v_cvt_f32_ubyte1_e32 v149, v227
	v_cvt_f32_ubyte0_e32 v148, v227
	v_pk_mul_f32 v[130:131], v[130:131], v[148:149]
	v_pk_mul_f32 v[132:133], v[144:145], v[146:147]
	v_pk_mul_f32 v[70:71], v[70:71], v[130:131]
	v_pk_mul_f32 v[72:73], v[72:73], v[132:133]
	s_waitcnt vmcnt(4)
;     __device__ __forceinline__ bf16_t* G() const { return (bf16_t*)(ws + OFF_G); }
; __device__ __forceinline__ float ub(unsigned w, int j) { return (float)((w >> (8 * j)) & 0xffu); }
;     __device__ __forceinline__ void operator()(int seg, f32x4 (&acc)[2][2][4][2]) const {
;     ...
;                 const int tk = tok0 + bj * 128 + wc * 32 + n * 16 + fr;
;                 const unsigned char* gprev = G + (size_t)tk * 3072 + (seg - 1) * 1024 + feat0 + wr * 64 + fq * 16;
; #pragma unroll
;                 for (int ai = 0; ai < 2; ai++) {
;                     const u32x4 gp = *(const u32x4*)(gprev + ai * 128), gn = *(const u32x4*)(gprev + 1024 + ai * 128);
; #pragma unroll
;                     for (int m = 0; m < 4; m++) {
;                         f32x4& v = acc[ai][bj][m][n];
;                         v[0] *= ub(gp[m], 0) * __builtin_amdgcn_rcpf(ub(gn[m], 0)); v[1] *= ub(gp[m], 1) * __builtin_amdgcn_rcpf(ub(gn[m], 1));
;                         v[2] *= ub(gp[m], 2) * __builtin_amdgcn_rcpf(ub(gn[m], 2)); v[3] *= ub(gp[m], 3) * __builtin_amdgcn_rcpf(ub(gn[m], 3));
;                     }
;                 }
	v_cvt_f32_ubyte1_e32 v151, v232
	v_cvt_f32_ubyte0_e32 v134, v236
	v_cvt_f32_ubyte1_e32 v135, v236
	v_rcp_iflag_f32_e32 v134, v134
	v_rcp_iflag_f32_e32 v135, v135
	v_cvt_f32_ubyte2_e32 v138, v236
	v_cvt_f32_ubyte3_e32 v139, v236
	v_cvt_f32_ubyte0_e32 v150, v232
	v_rcp_iflag_f32_e32 v138, v138
	v_rcp_iflag_f32_e32 v139, v139
	v_cvt_f32_ubyte3_e32 v149, v232
	v_cvt_f32_ubyte2_e32 v148, v232
	v_pk_mul_f32 v[134:135], v[134:135], v[150:151]
	v_cvt_f32_ubyte0_e32 v130, v237
	v_pk_mul_f32 v[30:31], v[30:31], v[134:135]
	v_rcp_iflag_f32_e32 v134, v130
	v_cvt_f32_ubyte1_e32 v130, v237
	v_rcp_iflag_f32_e32 v135, v130
	v_pk_mul_f32 v[138:139], v[138:139], v[148:149]
	v_cvt_f32_ubyte2_e32 v130, v237
	v_pk_mul_f32 v[32:33], v[32:33], v[138:139]
	v_rcp_iflag_f32_e32 v138, v130
	v_cvt_f32_ubyte3_e32 v130, v237
	v_cvt_f32_ubyte1_e32 v149, v233
	v_cvt_f32_ubyte0_e32 v148, v233
	v_rcp_iflag_f32_e32 v139, v130
	v_cvt_f32_ubyte3_e32 v145, v233
	v_cvt_f32_ubyte2_e32 v144, v233
	v_pk_mul_f32 v[130:131], v[134:135], v[148:149]
	v_pk_mul_f32 v[134:135], v[138:139], v[144:145]
	v_pk_mul_f32 v[22:23], v[22:23], v[130:131]
	v_cvt_f32_ubyte0_e32 v130, v238
	v_cvt_f32_ubyte1_e32 v131, v238
	v_rcp_iflag_f32_e32 v130, v130
	v_rcp_iflag_f32_e32 v131, v131
	v_pk_mul_f32 v[24:25], v[24:25], v[134:135]
	v_cvt_f32_ubyte2_e32 v134, v238
	v_cvt_f32_ubyte3_e32 v135, v238
	v_cvt_f32_ubyte1_e32 v145, v234
	v_cvt_f32_ubyte0_e32 v144, v234
	v_rcp_iflag_f32_e32 v134, v134
	v_rcp_iflag_f32_e32 v135, v135
	v_pk_mul_f32 v[130:131], v[130:131], v[144:145]
	v_cvt_f32_ubyte3_e32 v139, v234
	v_pk_mul_f32 v[14:15], v[14:15], v[130:131]
	v_cvt_f32_ubyte0_e32 v130, v239
	v_cvt_f32_ubyte1_e32 v131, v239
	v_rcp_iflag_f32_e32 v130, v130
	v_rcp_iflag_f32_e32 v131, v131
	v_cvt_f32_ubyte2_e32 v138, v234
	v_pk_mul_f32 v[134:135], v[134:135], v[138:139]
	v_cvt_f32_ubyte2_e32 v132, v239
	v_pk_mul_f32 v[16:17], v[16:17], v[134:135]
	v_rcp_iflag_f32_e32 v134, v132
	v_cvt_f32_ubyte3_e32 v132, v239
	v_cvt_f32_ubyte1_e32 v145, v235
	v_cvt_f32_ubyte0_e32 v144, v235
	v_rcp_iflag_f32_e32 v135, v132
	v_pk_mul_f32 v[130:131], v[130:131], v[144:145]
	v_cvt_f32_ubyte3_e32 v139, v235
	v_pk_mul_f32 v[6:7], v[6:7], v[130:131]
	v_or_b32_e32 v130, 0x90, v137
	v_mad_i64_i32 v[130:131], s[14:15], v130, s90, 0
	v_cvt_f32_ubyte2_e32 v138, v235
	v_or_b32_e32 v130, v130, v136
	v_pk_mul_f32 v[132:133], v[134:135], v[138:139]
	v_lshl_add_u64 v[134:135], s[10:11], 0, v[130:131]
	v_add_co_u32_e32 v144, vcc, s91, v134
	v_pk_mul_f32 v[8:9], v[8:9], v[132:133]
	s_nop 0
	v_addc_co_u32_e32 v145, vcc, 0, v135, vcc
	v_add_co_u32_e32 v134, vcc, s81, v134
	v_addc_co_u32_e32 v135, vcc, 0, v135, vcc
	s_waitcnt vmcnt(2)
;     __device__ __forceinline__ bf16_t* G() const { return (bf16_t*)(ws + OFF_G); }
; __device__ __forceinline__ float ub(unsigned w, int j) { return (float)((w >> (8 * j)) & 0xffu); }
;     __device__ __forceinline__ void operator()(int seg, f32x4 (&acc)[2][2][4][2]) const {
;     ...
;                 const int tk = tok0 + bj * 128 + wc * 32 + n * 16 + fr;
;                 const unsigned char* gprev = G + (size_t)tk * 3072 + (seg - 1) * 1024 + feat0 + wr * 64 + fq * 16;
; #pragma unroll
;                 for (int ai = 0; ai < 2; ai++) {
;                     const u32x4 gp = *(const u32x4*)(gprev + ai * 128), gn = *(const u32x4*)(gprev + 1024 + ai * 128);
; #pragma unroll
;                     for (int m = 0; m < 4; m++) {
;                         f32x4& v = acc[ai][bj][m][n];
;                         v[0] *= ub(gp[m], 0) * __builtin_amdgcn_rcpf(ub(gn[m], 0)); v[1] *= ub(gp[m], 1) * __builtin_amdgcn_rcpf(ub(gn[m], 1));
;                         v[2] *= ub(gp[m], 2) * __builtin_amdgcn_rcpf(ub(gn[m], 2)); v[3] *= ub(gp[m], 3) * __builtin_amdgcn_rcpf(ub(gn[m], 3));
;                     }
;                 }
	v_cvt_f32_ubyte1_e32 v153, v240
	v_cvt_f32_ubyte0_e32 v152, v240
	v_cvt_f32_ubyte3_e32 v151, v240
	v_cvt_f32_ubyte0_e32 v146, v244
	v_cvt_f32_ubyte1_e32 v147, v244
	v_rcp_iflag_f32_e32 v146, v146
	v_rcp_iflag_f32_e32 v147, v147
	v_cvt_f32_ubyte2_e32 v150, v240
	v_cvt_f32_ubyte0_e32 v130, v245
	v_cvt_f32_ubyte2_e32 v148, v244
	v_pk_mul_f32 v[146:147], v[146:147], v[152:153]
	v_cvt_f32_ubyte3_e32 v136, v244
	v_pk_mul_f32 v[90:91], v[90:91], v[146:147]
	v_rcp_iflag_f32_e32 v146, v130
	v_cvt_f32_ubyte1_e32 v130, v245
	v_rcp_iflag_f32_e32 v148, v148
	v_rcp_iflag_f32_e32 v149, v136
	v_rcp_iflag_f32_e32 v147, v130
	v_cvt_f32_ubyte2_e32 v130, v245
	v_rcp_iflag_f32_e32 v136, v130
	v_cvt_f32_ubyte3_e32 v130, v245
	v_rcp_iflag_f32_e32 v137, v130
	v_pk_mul_f32 v[148:149], v[148:149], v[150:151]
	v_cvt_f32_ubyte1_e32 v151, v241
	v_pk_mul_f32 v[92:93], v[92:93], v[148:149]
	v_cvt_f32_ubyte3_e32 v149, v241
	v_cvt_f32_ubyte2_e32 v148, v241
	v_cvt_f32_ubyte0_e32 v150, v241
	v_pk_mul_f32 v[130:131], v[146:147], v[150:151]
	v_pk_mul_f32 v[136:137], v[136:137], v[148:149]
	v_pk_mul_f32 v[82:83], v[82:83], v[130:131]
	v_pk_mul_f32 v[84:85], v[84:85], v[136:137]
	v_cvt_f32_ubyte0_e32 v130, v246
	v_cvt_f32_ubyte1_e32 v131, v246
	v_cvt_f32_ubyte2_e32 v136, v246
	v_cvt_f32_ubyte3_e32 v137, v246
	v_rcp_iflag_f32_e32 v130, v130
	v_rcp_iflag_f32_e32 v131, v131
	v_rcp_iflag_f32_e32 v136, v136
	v_rcp_iflag_f32_e32 v137, v137
	v_cvt_f32_ubyte3_e32 v147, v242
	v_cvt_f32_ubyte2_e32 v146, v242
	v_cvt_f32_ubyte1_e32 v149, v242
	v_cvt_f32_ubyte0_e32 v148, v242
	v_pk_mul_f32 v[130:131], v[130:131], v[148:149]
	v_pk_mul_f32 v[136:137], v[136:137], v[146:147]
	v_cvt_f32_ubyte2_e32 v132, v247
	v_pk_mul_f32 v[76:77], v[76:77], v[136:137]
	v_pk_mul_f32 v[74:75], v[74:75], v[130:131]
	v_cvt_f32_ubyte0_e32 v130, v247
	v_cvt_f32_ubyte1_e32 v131, v247
	v_rcp_iflag_f32_e32 v136, v132
	v_cvt_f32_ubyte3_e32 v132, v247
	v_rcp_iflag_f32_e32 v130, v130
	v_rcp_iflag_f32_e32 v131, v131
	v_rcp_iflag_f32_e32 v137, v132
	v_cvt_f32_ubyte3_e32 v139, v243
	v_cvt_f32_ubyte2_e32 v138, v243
	v_cvt_f32_ubyte1_e32 v147, v243
	v_cvt_f32_ubyte0_e32 v146, v243
	v_pk_mul_f32 v[130:131], v[130:131], v[146:147]
	v_pk_mul_f32 v[132:133], v[136:137], v[138:139]
	v_pk_mul_f32 v[66:67], v[66:67], v[130:131]
	v_pk_mul_f32 v[68:69], v[68:69], v[132:133]
	s_waitcnt vmcnt(0)
	v_cvt_f32_ubyte1_e32 v149, v156
	v_cvt_f32_ubyte0_e32 v138, v160
	v_cvt_f32_ubyte1_e32 v139, v160
	v_rcp_iflag_f32_e32 v138, v138
	v_rcp_iflag_f32_e32 v139, v139
	v_cvt_f32_ubyte0_e32 v148, v156
	v_cvt_f32_ubyte3_e32 v147, v156
	v_cvt_f32_ubyte2_e32 v146, v156
	v_pk_mul_f32 v[138:139], v[138:139], v[148:149]
	v_cvt_f32_ubyte0_e32 v130, v161
	v_cvt_f32_ubyte2_e32 v144, v160
	v_cvt_f32_ubyte3_e32 v134, v160
	v_pk_mul_f32 v[26:27], v[26:27], v[138:139]
	v_rcp_iflag_f32_e32 v138, v130
	v_cvt_f32_ubyte1_e32 v130, v161
	v_rcp_iflag_f32_e32 v144, v144
	v_rcp_iflag_f32_e32 v145, v134
	v_rcp_iflag_f32_e32 v139, v130
	v_cvt_f32_ubyte2_e32 v130, v161
	v_rcp_iflag_f32_e32 v134, v130
	v_cvt_f32_ubyte3_e32 v130, v161
	v_rcp_iflag_f32_e32 v135, v130
	v_pk_mul_f32 v[144:145], v[144:145], v[146:147]
	v_cvt_f32_ubyte1_e32 v147, v157
	v_pk_mul_f32 v[28:29], v[28:29], v[144:145]
	v_cvt_f32_ubyte3_e32 v145, v157
	v_cvt_f32_ubyte2_e32 v144, v157
	v_cvt_f32_ubyte0_e32 v146, v157
	v_pk_mul_f32 v[130:131], v[138:139], v[146:147]
	v_pk_mul_f32 v[134:135], v[134:135], v[144:145]
	v_pk_mul_f32 v[18:19], v[18:19], v[130:131]
	v_pk_mul_f32 v[20:21], v[20:21], v[134:135]
	v_cvt_f32_ubyte0_e32 v130, v162
	v_cvt_f32_ubyte1_e32 v131, v162
	v_cvt_f32_ubyte2_e32 v134, v162
	v_cvt_f32_ubyte3_e32 v135, v162
	v_rcp_iflag_f32_e32 v130, v130
	v_rcp_iflag_f32_e32 v131, v131
	v_rcp_iflag_f32_e32 v134, v134
	v_rcp_iflag_f32_e32 v135, v135
	v_cvt_f32_ubyte3_e32 v139, v158
	v_cvt_f32_ubyte2_e32 v138, v158
	v_cvt_f32_ubyte1_e32 v145, v158
	v_cvt_f32_ubyte0_e32 v144, v158
	v_pk_mul_f32 v[130:131], v[130:131], v[144:145]
	v_pk_mul_f32 v[134:135], v[134:135], v[138:139]
	v_cvt_f32_ubyte2_e32 v132, v163
	v_pk_mul_f32 v[12:13], v[12:13], v[134:135]
	v_pk_mul_f32 v[10:11], v[10:11], v[130:131]
	v_cvt_f32_ubyte0_e32 v130, v163
	v_cvt_f32_ubyte1_e32 v131, v163
	v_rcp_iflag_f32_e32 v134, v132
	v_cvt_f32_ubyte3_e32 v132, v163
	v_rcp_iflag_f32_e32 v130, v130
	v_rcp_iflag_f32_e32 v131, v131
	v_rcp_iflag_f32_e32 v135, v132
	v_cvt_f32_ubyte3_e32 v137, v159
	v_cvt_f32_ubyte2_e32 v136, v159
	v_cvt_f32_ubyte1_e32 v139, v159
	v_cvt_f32_ubyte0_e32 v138, v159
	v_pk_mul_f32 v[130:131], v[130:131], v[138:139]
	v_pk_mul_f32 v[132:133], v[134:135], v[136:137]
	v_pk_mul_f32 v[2:3], v[2:3], v[130:131]
	v_pk_mul_f32 v[4:5], v[4:5], v[132:133]
